# adds: P5 first-K-iteration waits relaxed (prologue drains all, epilogue load waits imply older DMA completion; spurious compiler vmcnt waits removed)
# speedup vs baseline: 1.0068x; 1.0068x over previous
; __host__ __device__ __forceinline__ size_t tl_off(int row, int k, int K) { return ((((size_t)(row >> 4) * (size_t)(K >> 5)) + (size_t)(k >> 5)) << 9) + (size_t)((row & 15) * 32 + (k & 31)); }
;     __host__ __device__ bool next(int i, Unit& u) const { const bool ok = StaticOrder::next(i, u); if (ok) u.pm = nM - 1 - u.pm; return ok; }
; #define PG8_STAGE(bufoff, gbase, voff) do { _Pragma("unroll") for (int _i = 0; _i < 2; ++_i) \
;         asm volatile("s_mov_b32 m0, %2\n\ts_nop 0\n\tglobal_load_lds_dwordx4 %0, %1" :: "v"((voff)[_i]), "s"((const char*)(gbase)), "s"(ldsbase + (unsigned)((bufoff) + _i * 8192)) : "memory"); } while (0)
; #define PG8_WAIT_V(n) asm volatile("s_waitcnt vmcnt(" #n ")" ::: "memory")
; #define PG8_BAR __builtin_amdgcn_s_barrier()
;     ...
;     for (int i = 0; i < 2; ++i) { int R, C; stage_rc(tid * 16 + i * 8192, R, C); const int Rb = Epi::PERM ? ((R & ~31) + perm32(R & 31)) : R;
;         voffA[i] = A_TILED ? (unsigned)tl_off(R, C, K) * 2u : (unsigned)(R * K + C) * 2u; voffB[i] = (unsigned)tl_off(Rb, C, K) * 2u; }
;     const size_t kstepA = A_TILED ? (size_t)2048 : (size_t)(BK * 2), kstepB = 2048;
;     const size_t hstep = (size_t)HALF * K * 2;
;     const size_t tstep = 2 * hstep;
;     const unsigned ldsw = (unsigned)wid * 1024u;
;     const unsigned ldsbase = (unsigned)(size_t)lds + ldsw;
;     const int aoff = lds_byte(wr * 64 + fr, fq * 8), boff = lds_byte(wc * 32 + fr, fq * 8);
;     ...
;     const unsigned sc8w = g.sw8, sc8a = g.sa8;
;     Unit cur, nxt; int ui = 0;
;     if (!S.next(0, cur)) return;
;     f32x4 acc[2][2][4][2];
;     bf16x8 At[4][2], B0[2][2], B1[2][2];
;     const char* cA = (const char*)g.A + (size_t)cur.pm * tstep; const char* cB = (const char*)g.Bt + (size_t)cur.pn * tstep;
;     S.a_ready(cur);
;     PG8_STAGE(PG8_SB(0, 0), cB, voffB); PG8_STAGE(PG8_SB(0, 1), cB + hstep, voffB); PG8_STAGE(PG8_SA(0, 0), cA, voffA); PG8_STAGE(PG8_SA(0, 1), cA + hstep, voffA);
;     if (wr == 1) PG8_BAR;
;     PG8_WAIT_V(2); PG8_BAR;
;     PG8_STAGE(PG8_SB(1, 0), cB + kstepB, voffB); PG8_STAGE(PG8_SA(1, 0), cA + kstepA, voffA); PG8_STAGE(PG8_SB(1, 1), cB + hstep + kstepB, voffB);
;     PG8_WAIT_V(6); PG8_BAR;
.LBB0_557:
	v_bfe_u32 v159, v0, 4, 2
	v_and_b32_e32 v158, 15, v0
	v_lshlrev_b32_e32 v1, 4, v159
	v_lshlrev_b32_e32 v0, 2, v0
	s_lshl_b32 s42, s0, 6
	v_lshl_or_b32 v1, v158, 6, v1
	s_lshl_b32 s0, s0, 13
	v_and_b32_e32 v0, 32, v0
	v_bitop3_b32 v2, v1, s0, v0 bitop3:0xde
	s_lshl_b32 s0, s10, 5
	s_and_b32 s43, s0, 0x60
	s_lshl_b32 s0, s43, 7
	v_bitop3_b32 v0, v1, s0, v0 bitop3:0xde
	s_add_u32 s0, s16, 0x800
	s_sext_i32_i8 s76, s1
	s_waitcnt vmcnt(2)
	s_barrier
	s_addc_u32 s1, s17, 0
	s_add_i32 s44, s30, 0x18000
	s_mov_b32 m0, s44
	s_nop 0
	global_load_lds_dwordx4 v155, s[0:1]
	s_add_i32 s45, s30, 0x1a000
	s_mov_b32 m0, s45
	s_nop 0
	global_load_lds_dwordx4 v157, s[0:1]
	s_add_u32 s0, s18, 0x800
	s_addc_u32 s1, s19, 0
	s_add_i32 s46, s30, 0x8000
	s_mov_b32 m0, s46
	s_nop 0
	global_load_lds_dwordx4 v154, s[0:1]
	s_add_i32 s47, s30, 0xa000
	s_mov_b32 m0, s47
	s_nop 0
	global_load_lds_dwordx4 v156, s[0:1]
	s_add_u32 s0, s16, 0xb0800
	s_addc_u32 s1, s17, 0
	s_add_i32 s48, s30, 0x1c000
	s_mov_b32 m0, s48
	s_nop 0
	global_load_lds_dwordx4 v155, s[0:1]
	s_add_i32 s49, s30, 0x1e000
	s_mov_b32 m0, s49
	s_nop 0
	global_load_lds_dwordx4 v157, s[0:1]
	s_waitcnt vmcnt(0)
	s_add_i32 s50, s30, 0xc000
	s_cmpk_lt_u32 s4, 0x100
	v_add_u32_e32 v0, 0, v0
	s_cselect_b64 s[10:11], -1, 0
	s_add_i32 s51, s30, 0xe000
	s_ashr_i32 s52, s3, 31
	v_mov_b64_e32 v[144:145], 0x400
	v_mov_b64_e32 v[146:147], 0x3ff
	v_add_u32_e32 v160, 0x10000, v0
	v_add_u32_e32 v161, 0x14000, v0
	v_add_u32_e32 v162, 0, v2
	v_add_u32_e32 v163, 0x18000, v0
	v_add_u32_e32 v164, 0x1c000, v0
	v_mov_b32_e32 v149, 0
	s_movk_i32 s53, 0x1000
	s_mov_b32 s54, 0x9000
	s_mov_b32 s55, 0x11000
	s_mov_b32 s56, 0x19000
	s_mov_b32 s57, 0x41000
	s_mov_b32 s58, 0x49000
	s_mov_b32 s59, 0x20000
	s_mov_b32 s60, 0x21000
	s_mov_b32 s61, 0x51000
	s_mov_b32 s62, 0x30000
	s_mov_b32 s63, 0x31000
	s_mov_b32 s64, 0x59000
	s_mov_b32 s65, 0x80000
	s_mov_b32 s66, 0x81000
	s_mov_b32 s67, 0x90000
	s_mov_b32 s68, 0x91000
	s_mov_b32 s69, 0xa0000
	s_mov_b32 s70, 0xa1000
	s_mov_b32 s71, 0xb0000
	s_mov_b32 s72, 0xb1000
	s_barrier
	s_branch .LBB0_560

.LBB0_570:
	ds_read_b128 v[0:3], v160
	ds_read_b128 v[4:7], v160 offset:1024
	s_waitcnt lgkmcnt(6)
	ds_read_b128 v[8:11], v160 offset:2048
	s_waitcnt lgkmcnt(3)
	ds_read_b128 v[12:15], v160 offset:3072
	ds_read_b128 v[16:19], v161
	ds_read_b128 v[20:23], v161 offset:1024
	ds_read_b128 v[24:27], v161 offset:2048
	ds_read_b128 v[28:31], v161 offset:3072
	s_add_u32 s4, s18, 0x1000
	s_addc_u32 s5, s19, 0
	s_add_u32 s20, s18, 0x1800
	s_addc_u32 s21, s19, 0
	s_add_u32 s22, s16, 0x1000
	s_addc_u32 s23, s17, 0
	ds_read_b128 v[32:35], v162
	ds_read_b128 v[36:39], v162 offset:1024
	ds_read_b128 v[40:43], v162 offset:2048
	ds_read_b128 v[44:47], v162 offset:3072
	ds_read_b128 v[48:51], v162 offset:4096
	ds_read_b128 v[52:55], v162 offset:5120
	ds_read_b128 v[56:59], v162 offset:6144
	ds_read_b128 v[60:63], v162 offset:7168
	s_add_u32 s78, s18, 0xb0800
	s_addc_u32 s79, s19, 0
	s_mov_b32 m0, s50
	s_nop 0
	global_load_lds_dwordx4 v154, s[78:79]
	s_mov_b32 m0, s51
	s_nop 0
	global_load_lds_dwordx4 v156, s[78:79]
	s_nop 0
	s_waitcnt lgkmcnt(0)
	s_barrier
	s_setprio 1
	s_waitcnt lgkmcnt(7)
	v_mfma_f32_16x16x32_bf16 v[64:67], v[0:3], v[32:35], 0
	v_mfma_f32_16x16x32_bf16 v[68:71], v[8:11], v[32:35], 0
	s_waitcnt lgkmcnt(5)
	v_mfma_f32_16x16x32_bf16 v[72:75], v[0:3], v[40:43], 0
	v_mfma_f32_16x16x32_bf16 v[76:79], v[8:11], v[40:43], 0
	s_waitcnt lgkmcnt(3)
	v_mfma_f32_16x16x32_bf16 v[80:83], v[0:3], v[48:51], 0
	v_mfma_f32_16x16x32_bf16 v[84:87], v[8:11], v[48:51], 0
	s_waitcnt lgkmcnt(1)
	v_mfma_f32_16x16x32_bf16 v[96:99], v[0:3], v[56:59], 0
	v_mfma_f32_16x16x32_bf16 v[100:103], v[8:11], v[56:59], 0
	v_mfma_f32_16x16x32_bf16 v[64:67], v[4:7], v[36:39], v[64:67]
	v_mfma_f32_16x16x32_bf16 v[68:71], v[12:15], v[36:39], v[68:71]
	v_mfma_f32_16x16x32_bf16 v[72:75], v[4:7], v[44:47], v[72:75]
	v_mfma_f32_16x16x32_bf16 v[76:79], v[12:15], v[44:47], v[76:79]
	v_mfma_f32_16x16x32_bf16 v[80:83], v[4:7], v[52:55], v[80:83]
	v_mfma_f32_16x16x32_bf16 v[84:87], v[12:15], v[52:55], v[84:87]
	s_waitcnt lgkmcnt(0)
	v_mfma_f32_16x16x32_bf16 v[96:99], v[4:7], v[60:63], v[96:99]
	v_mfma_f32_16x16x32_bf16 v[100:103], v[12:15], v[60:63], v[100:103]
	s_setprio 0
	s_setprio 1
	v_mfma_f32_16x16x32_bf16 v[112:115], v[16:19], v[32:35], 0
	v_mfma_f32_16x16x32_bf16 v[128:131], v[24:27], v[32:35], 0
	v_mfma_f32_16x16x32_bf16 v[32:35], v[16:19], v[40:43], 0
	v_mfma_f32_16x16x32_bf16 v[132:135], v[24:27], v[40:43], 0
	v_mfma_f32_16x16x32_bf16 v[40:43], v[16:19], v[48:51], 0
	v_mfma_f32_16x16x32_bf16 v[136:139], v[24:27], v[48:51], 0
	v_mfma_f32_16x16x32_bf16 v[48:51], v[16:19], v[56:59], 0
	v_mfma_f32_16x16x32_bf16 v[140:143], v[24:27], v[56:59], 0
	s_nop 0
	v_mfma_f32_16x16x32_bf16 v[112:115], v[20:23], v[36:39], v[112:115]
	v_mfma_f32_16x16x32_bf16 v[128:131], v[28:31], v[36:39], v[128:131]
	v_mfma_f32_16x16x32_bf16 v[32:35], v[20:23], v[44:47], v[32:35]
	v_mfma_f32_16x16x32_bf16 v[132:135], v[28:31], v[44:47], v[132:135]
	v_mfma_f32_16x16x32_bf16 v[40:43], v[20:23], v[52:55], v[40:43]
	v_mfma_f32_16x16x32_bf16 v[136:139], v[28:31], v[52:55], v[136:139]
	v_mfma_f32_16x16x32_bf16 v[48:51], v[20:23], v[60:63], v[48:51]
	v_mfma_f32_16x16x32_bf16 v[140:143], v[28:31], v[60:63], v[140:143]
	s_setprio 0
	s_barrier
	ds_read_b128 v[36:39], v162 offset:16384
	ds_read_b128 v[44:47], v162 offset:17408
	ds_read_b128 v[52:55], v162 offset:18432
	ds_read_b128 v[56:59], v162 offset:19456
	ds_read_b128 v[60:63], v162 offset:20480
	ds_read_b128 v[88:91], v162 offset:21504
	s_nop 0
	ds_read_b128 v[92:95], v162 offset:22528
	ds_read_b128 v[104:107], v162 offset:23552
	s_mov_b32 m0, s33
	s_nop 0
	global_load_lds_dwordx4 v155, s[22:23]
	s_mov_b32 m0, s36
	s_nop 0
	global_load_lds_dwordx4 v157, s[22:23]
	s_add_u32 s22, s16, 0xb1000
	s_addc_u32 s23, s17, 0
	s_mov_b32 m0, s37
	s_nop 0
	global_load_lds_dwordx4 v155, s[22:23]
	s_mov_b32 m0, s38
	s_nop 0
	global_load_lds_dwordx4 v157, s[22:23]
	s_mov_b32 m0, s30
	s_nop 0
	global_load_lds_dwordx4 v154, s[4:5]
	s_mov_b32 m0, s39
	s_nop 0
	global_load_lds_dwordx4 v156, s[4:5]
	s_nop 0
	s_waitcnt lgkmcnt(0)
	s_barrier
	s_setprio 1
	s_waitcnt lgkmcnt(7)
	v_mfma_f32_16x16x32_bf16 v[150:153], v[0:3], v[36:39], 0
	v_mfma_f32_16x16x32_bf16 v[166:169], v[8:11], v[36:39], 0
	s_waitcnt lgkmcnt(5)
	v_mfma_f32_16x16x32_bf16 v[170:173], v[0:3], v[52:55], 0
	v_mfma_f32_16x16x32_bf16 v[174:177], v[8:11], v[52:55], 0
	s_waitcnt lgkmcnt(3)
	v_mfma_f32_16x16x32_bf16 v[178:181], v[0:3], v[60:63], 0
	v_mfma_f32_16x16x32_bf16 v[182:185], v[8:11], v[60:63], 0
	s_waitcnt lgkmcnt(1)
	v_mfma_f32_16x16x32_bf16 v[186:189], v[0:3], v[92:95], 0
	v_mfma_f32_16x16x32_bf16 v[0:3], v[8:11], v[92:95], 0
	v_mfma_f32_16x16x32_bf16 v[150:153], v[4:7], v[44:47], v[150:153]
	v_mfma_f32_16x16x32_bf16 v[166:169], v[12:15], v[44:47], v[166:169]
	v_mfma_f32_16x16x32_bf16 v[170:173], v[4:7], v[56:59], v[170:173]
	v_mfma_f32_16x16x32_bf16 v[174:177], v[12:15], v[56:59], v[174:177]
	v_mfma_f32_16x16x32_bf16 v[178:181], v[4:7], v[88:91], v[178:181]
	v_mfma_f32_16x16x32_bf16 v[182:185], v[12:15], v[88:91], v[182:185]
	s_waitcnt lgkmcnt(0)
	v_mfma_f32_16x16x32_bf16 v[186:189], v[4:7], v[104:107], v[186:189]
	v_mfma_f32_16x16x32_bf16 v[0:3], v[12:15], v[104:107], v[0:3]
	s_setprio 0
	s_setprio 1
	v_mfma_f32_16x16x32_bf16 v[4:7], v[16:19], v[36:39], 0
	v_mfma_f32_16x16x32_bf16 v[190:193], v[24:27], v[36:39], 0
	v_mfma_f32_16x16x32_bf16 v[36:39], v[16:19], v[52:55], 0
	v_mfma_f32_16x16x32_bf16 v[194:197], v[24:27], v[52:55], 0
	v_mfma_f32_16x16x32_bf16 v[198:201], v[16:19], v[60:63], 0
	v_mfma_f32_16x16x32_bf16 v[202:205], v[24:27], v[60:63], 0
	v_mfma_f32_16x16x32_bf16 v[206:209], v[16:19], v[92:95], 0
	v_mfma_f32_16x16x32_bf16 v[210:213], v[24:27], v[92:95], 0
	s_nop 0
	v_mfma_f32_16x16x32_bf16 v[4:7], v[20:23], v[44:47], v[4:7]
	v_mfma_f32_16x16x32_bf16 v[190:193], v[28:31], v[44:47], v[190:193]
	v_mfma_f32_16x16x32_bf16 v[36:39], v[20:23], v[56:59], v[36:39]
	v_mfma_f32_16x16x32_bf16 v[194:197], v[28:31], v[56:59], v[194:197]
	v_mfma_f32_16x16x32_bf16 v[198:201], v[20:23], v[88:91], v[198:201]
	v_mfma_f32_16x16x32_bf16 v[202:205], v[28:31], v[88:91], v[202:205]
	v_mfma_f32_16x16x32_bf16 v[206:209], v[20:23], v[104:107], v[206:209]
	v_mfma_f32_16x16x32_bf16 v[210:213], v[28:31], v[104:107], v[210:213]
	s_setprio 0
	s_barrier
	ds_read_b128 v[8:11], v163
	ds_read_b128 v[12:15], v163 offset:1024
	ds_read_b128 v[16:19], v163 offset:2048
	ds_read_b128 v[20:23], v163 offset:3072
	ds_read_b128 v[214:217], v164
	ds_read_b128 v[218:221], v164 offset:1024
	ds_read_b128 v[222:225], v164 offset:2048
	ds_read_b128 v[226:229], v164 offset:3072
	ds_read_b128 v[24:27], v162 offset:32768
	ds_read_b128 v[28:31], v162 offset:33792
	ds_read_b128 v[44:47], v162 offset:34816
	ds_read_b128 v[52:55], v162 offset:35840
	ds_read_b128 v[56:59], v162 offset:36864
	ds_read_b128 v[60:63], v162 offset:37888
	ds_read_b128 v[230:233], v162 offset:38912
	ds_read_b128 v[234:237], v162 offset:39936
	s_add_u32 s18, s18, 0xb1000
	s_addc_u32 s19, s19, 0
	s_mov_b32 m0, s40
	s_nop 0
	global_load_lds_dwordx4 v154, s[18:19]
	s_mov_b32 m0, s41
	s_nop 0
	global_load_lds_dwordx4 v156, s[18:19]
	s_waitcnt vmcnt(8)
	s_waitcnt lgkmcnt(0)
	s_barrier
	s_setprio 1
	s_waitcnt lgkmcnt(7)
	v_mfma_f32_16x16x32_bf16 v[64:67], v[8:11], v[24:27], v[64:67]
	s_waitcnt lgkmcnt(6)
	v_mfma_f32_16x16x32_bf16 v[124:127], v[12:15], v[28:31], v[64:67]
	v_mfma_f32_16x16x32_bf16 v[64:67], v[16:19], v[24:27], v[68:71]
	v_mfma_f32_16x16x32_bf16 v[120:123], v[20:23], v[28:31], v[64:67]
	s_waitcnt lgkmcnt(5)
	v_mfma_f32_16x16x32_bf16 v[64:67], v[8:11], v[44:47], v[72:75]
	s_waitcnt lgkmcnt(4)
	v_mfma_f32_16x16x32_bf16 v[108:111], v[12:15], v[52:55], v[64:67]
	v_mfma_f32_16x16x32_bf16 v[64:67], v[16:19], v[44:47], v[76:79]
	v_mfma_f32_16x16x32_bf16 v[104:107], v[20:23], v[52:55], v[64:67]
	s_waitcnt lgkmcnt(3)
	v_mfma_f32_16x16x32_bf16 v[64:67], v[8:11], v[56:59], v[80:83]
	s_waitcnt lgkmcnt(2)
	v_mfma_f32_16x16x32_bf16 v[92:95], v[12:15], v[60:63], v[64:67]
	v_mfma_f32_16x16x32_bf16 v[64:67], v[16:19], v[56:59], v[84:87]
	v_mfma_f32_16x16x32_bf16 v[88:91], v[20:23], v[60:63], v[64:67]
	s_waitcnt lgkmcnt(1)
	v_mfma_f32_16x16x32_bf16 v[64:67], v[8:11], v[230:233], v[96:99]
	s_waitcnt lgkmcnt(0)
	v_mfma_f32_16x16x32_bf16 v[76:79], v[12:15], v[234:237], v[64:67]
	v_mfma_f32_16x16x32_bf16 v[64:67], v[16:19], v[230:233], v[100:103]
	v_mfma_f32_16x16x32_bf16 v[72:75], v[20:23], v[234:237], v[64:67]
	s_setprio 0
	s_setprio 1
	v_mfma_f32_16x16x32_bf16 v[64:67], v[214:217], v[24:27], v[112:115]
	v_mfma_f32_16x16x32_bf16 v[24:27], v[222:225], v[24:27], v[128:131]
	v_mfma_f32_16x16x32_bf16 v[112:115], v[226:229], v[28:31], v[24:27]
	v_mfma_f32_16x16x32_bf16 v[24:27], v[214:217], v[44:47], v[32:35]
	v_mfma_f32_16x16x32_bf16 v[100:103], v[218:221], v[52:55], v[24:27]
	v_mfma_f32_16x16x32_bf16 v[24:27], v[222:225], v[44:47], v[132:135]
	v_mfma_f32_16x16x32_bf16 v[96:99], v[226:229], v[52:55], v[24:27]
	v_mfma_f32_16x16x32_bf16 v[24:27], v[214:217], v[56:59], v[40:43]
	v_mfma_f32_16x16x32_bf16 v[84:87], v[218:221], v[60:63], v[24:27]
	v_mfma_f32_16x16x32_bf16 v[24:27], v[222:225], v[56:59], v[136:139]
	v_mfma_f32_16x16x32_bf16 v[80:83], v[226:229], v[60:63], v[24:27]
	v_mfma_f32_16x16x32_bf16 v[24:27], v[214:217], v[230:233], v[48:51]
	v_mfma_f32_16x16x32_bf16 v[68:71], v[218:221], v[234:237], v[24:27]
	v_mfma_f32_16x16x32_bf16 v[24:27], v[222:225], v[230:233], v[140:143]
	v_mfma_f32_16x16x32_bf16 v[116:119], v[218:221], v[28:31], v[64:67]
	v_mfma_f32_16x16x32_bf16 v[64:67], v[226:229], v[234:237], v[24:27]
	s_setprio 0
	s_barrier
	ds_read_b128 v[32:35], v162 offset:49152
	ds_read_b128 v[48:51], v162 offset:50176
	ds_read_b128 v[128:131], v162 offset:51200
	ds_read_b128 v[132:135], v162 offset:52224
	ds_read_b128 v[136:139], v162 offset:53248
	ds_read_b128 v[140:143], v162 offset:54272
	ds_read_b128 v[230:233], v162 offset:55296
	ds_read_b128 v[234:237], v162 offset:56320
	s_add_u32 s18, s16, 0x1800
	s_addc_u32 s19, s17, 0
	s_mov_b32 m0, s44
	s_nop 0
	global_load_lds_dwordx4 v155, s[18:19]
	s_mov_b32 m0, s45
	s_nop 0
	global_load_lds_dwordx4 v157, s[18:19]
	s_add_u32 s18, s16, 0xb1800
	s_addc_u32 s19, s17, 0
	s_mov_b32 m0, s48
	s_nop 0
	global_load_lds_dwordx4 v155, s[18:19]
	s_mov_b32 m0, s49
	s_nop 0
	global_load_lds_dwordx4 v157, s[18:19]
	s_mov_b32 m0, s46
	s_nop 0
	global_load_lds_dwordx4 v154, s[20:21]
	s_mov_b32 m0, s47
	s_nop 0
	global_load_lds_dwordx4 v156, s[20:21]
	s_waitcnt vmcnt(8)
	s_waitcnt lgkmcnt(0)
	s_barrier
	s_setprio 1
	s_waitcnt lgkmcnt(7)
	v_mfma_f32_16x16x32_bf16 v[24:27], v[8:11], v[32:35], v[150:153]
	s_waitcnt lgkmcnt(6)
	v_mfma_f32_16x16x32_bf16 v[60:63], v[12:15], v[48:51], v[24:27]
	v_mfma_f32_16x16x32_bf16 v[24:27], v[16:19], v[32:35], v[166:169]
	v_mfma_f32_16x16x32_bf16 v[56:59], v[20:23], v[48:51], v[24:27]
	s_waitcnt lgkmcnt(5)
	v_mfma_f32_16x16x32_bf16 v[24:27], v[8:11], v[128:131], v[170:173]
	s_waitcnt lgkmcnt(4)
	v_mfma_f32_16x16x32_bf16 v[44:47], v[12:15], v[132:135], v[24:27]
	v_mfma_f32_16x16x32_bf16 v[24:27], v[16:19], v[128:131], v[174:177]
	v_mfma_f32_16x16x32_bf16 v[40:43], v[20:23], v[132:135], v[24:27]
	s_waitcnt lgkmcnt(3)
	v_mfma_f32_16x16x32_bf16 v[24:27], v[8:11], v[136:139], v[178:181]
	s_waitcnt lgkmcnt(2)
	v_mfma_f32_16x16x32_bf16 v[28:31], v[12:15], v[140:143], v[24:27]
	v_mfma_f32_16x16x32_bf16 v[24:27], v[16:19], v[136:139], v[182:185]
	s_waitcnt lgkmcnt(1)
	v_mfma_f32_16x16x32_bf16 v[8:11], v[8:11], v[230:233], v[186:189]
	v_mfma_f32_16x16x32_bf16 v[0:3], v[16:19], v[230:233], v[0:3]
	v_mfma_f32_16x16x32_bf16 v[24:27], v[20:23], v[140:143], v[24:27]
	s_waitcnt lgkmcnt(0)
	v_mfma_f32_16x16x32_bf16 v[12:15], v[12:15], v[234:237], v[8:11]
	v_mfma_f32_16x16x32_bf16 v[8:11], v[20:23], v[234:237], v[0:3]
	s_setprio 0
	s_setprio 1
	v_mfma_f32_16x16x32_bf16 v[0:3], v[214:217], v[32:35], v[4:7]
	v_mfma_f32_16x16x32_bf16 v[52:55], v[218:221], v[48:51], v[0:3]
	v_mfma_f32_16x16x32_bf16 v[0:3], v[222:225], v[32:35], v[190:193]
	v_mfma_f32_16x16x32_bf16 v[48:51], v[226:229], v[48:51], v[0:3]
	v_mfma_f32_16x16x32_bf16 v[0:3], v[214:217], v[128:131], v[36:39]
	v_mfma_f32_16x16x32_bf16 v[36:39], v[218:221], v[132:135], v[0:3]
	v_mfma_f32_16x16x32_bf16 v[0:3], v[222:225], v[128:131], v[194:197]
	v_mfma_f32_16x16x32_bf16 v[32:35], v[226:229], v[132:135], v[0:3]
	v_mfma_f32_16x16x32_bf16 v[0:3], v[214:217], v[136:139], v[198:201]
	v_mfma_f32_16x16x32_bf16 v[20:23], v[218:221], v[140:143], v[0:3]
	v_mfma_f32_16x16x32_bf16 v[0:3], v[222:225], v[136:139], v[202:205]
	v_mfma_f32_16x16x32_bf16 v[16:19], v[226:229], v[140:143], v[0:3]
	v_mfma_f32_16x16x32_bf16 v[0:3], v[214:217], v[230:233], v[206:209]
	v_mfma_f32_16x16x32_bf16 v[4:7], v[218:221], v[234:237], v[0:3]
	v_mfma_f32_16x16x32_bf16 v[0:3], v[222:225], v[230:233], v[210:213]
	v_mfma_f32_16x16x32_bf16 v[0:3], v[226:229], v[234:237], v[0:3]
	s_setprio 0
	s_barrier
	s_add_u32 s77, s16, 0x2000
	s_addc_u32 s78, s17, 0
	s_mov_b32 s79, 0
